# v8 + merge GEMM (P4) K-split sample-row epilogue de-serialised: 16 fp8 gate loads hoisted with their row addresses, one wait (was load-wait-2 stores x16)
# speedup vs baseline: 1.0068x; 1.0068x over previous
;     __device__ __forceinline__ void operator()(Acc& acc, const Unit& u, int wr, int wc, int fr, int fq) const {
;         if (u.part) {
;             const unsigned char* sg = (const unsigned char*)(u.sub == 0 ? (const bf16_t*)za : zb) + (size_t)(u.pm * 256 + wr * 64 + fr) * DM + u.pn * 256 + wc * 32 + 8 * fq;
;             float* sl = slab + ((size_t)(u.part - 1) * MS + (u.pm * 256 - MP) + wr * 64 + fr) * DM + u.pn * 256 + wc * 32 + 8 * fq;
; #pragma unroll
;             for (int ai = 0; ai < 2; ++ai)
; #pragma unroll
;                 for (int m = 0; m < 4; ++m)
; #pragma unroll
;                     for (int bj = 0; bj < 2; ++bj) { const size_t ro = (size_t)(ai * HALF + m * 16) * DM + bj * HALF;
;                         f32x4 g0, g1; fp8x8_to_f32(*(const u32x2*)(sg + ro), g0, g1);
;                         *(f32x4*)(sl + ro) = acc[ai][bj][m][0] * (1.0f / (O_SCALE * WO_SCALE * G_SCALE)) * g0;
;                         *(f32x4*)(sl + ro + 4) = acc[ai][bj][m][1] * (1.0f / (O_SCALE * WO_SCALE * G_SCALE)) * g1; }
.LBB0_2061:
	s_cmp_eq_u32 s48, 0
	s_cselect_b64 s[66:67], -1, 0
	s_cmp_lg_u32 s48, 0
	s_cselect_b64 s[64:65], -1, 0
	s_cmp_eq_u32 s28, 0
	s_cbranch_scc1 .LBB0_2063
	s_and_b64 s[42:43], s[66:67], exec
	s_cselect_b32 s43, s59, s61
	s_cselect_b32 s42, s58, s60
	s_lshl_b32 s3, s10, 8
	v_add_u32_e32 v128, s3, v168
	v_ashrrev_i32_e32 v129, 31, v128
	v_lshlrev_b64 v[128:129], 11, v[128:129]
	v_lshl_add_u64 v[128:129], s[42:43], 0, v[128:129]
	s_lshl_b32 s42, s8, 8
	s_ashr_i32 s43, s42, 31
	v_lshl_add_u64 v[128:129], v[128:129], 0, s[42:43]
	v_lshl_add_u64 v[128:129], v[128:129], 0, s[18:19]
	v_lshl_add_u64 v[130:131], v[128:129], 0, v[170:171]
	v_add_co_u32_e32 v196, vcc, 0x8000, v130
	s_nop 1
	v_addc_co_u32_e32 v197, vcc, 0, v131, vcc
	v_add_co_u32_e32 v198, vcc, 0x10000, v130
	s_nop 1
	v_addc_co_u32_e32 v199, vcc, 0, v131, vcc
	v_add_co_u32_e32 v200, vcc, 0x18000, v130
	s_nop 1
	v_addc_co_u32_e32 v201, vcc, 0, v131, vcc
	v_add_co_u32_e32 v202, vcc, 0x40000, v130
	s_nop 1
	v_addc_co_u32_e32 v203, vcc, 0, v131, vcc
	v_add_co_u32_e32 v204, vcc, 0x48000, v130
	s_nop 1
	v_addc_co_u32_e32 v205, vcc, 0, v131, vcc
	v_add_co_u32_e32 v206, vcc, 0x50000, v130
	s_nop 1
	v_addc_co_u32_e32 v207, vcc, 0, v131, vcc
	v_add_co_u32_e32 v208, vcc, 0x58000, v130
	s_nop 1
	v_addc_co_u32_e32 v209, vcc, 0, v131, vcc
	global_load_dwordx2 v[210:211], v[130:131], off
	global_load_dwordx2 v[212:213], v[130:131], off offset:128
	global_load_dwordx2 v[214:215], v[196:197], off
	global_load_dwordx2 v[216:217], v[196:197], off offset:128
	global_load_dwordx2 v[218:219], v[198:199], off
	global_load_dwordx2 v[220:221], v[198:199], off offset:128
	global_load_dwordx2 v[222:223], v[200:201], off
	global_load_dwordx2 v[224:225], v[200:201], off offset:128
	global_load_dwordx2 v[226:227], v[202:203], off
	global_load_dwordx2 v[228:229], v[202:203], off offset:128
	global_load_dwordx2 v[230:231], v[204:205], off
	global_load_dwordx2 v[232:233], v[204:205], off offset:128
	global_load_dwordx2 v[234:235], v[206:207], off
	global_load_dwordx2 v[236:237], v[206:207], off offset:128
	global_load_dwordx2 v[238:239], v[208:209], off
	global_load_dwordx2 v[240:241], v[208:209], off offset:128
	s_ashr_i32 s29, s28, 31
	s_add_i32 s90, s3, 0xffff8000
	s_lshl_b64 s[68:69], s[28:29], 22
	s_ashr_i32 s91, s90, 31
	v_lshl_add_u64 v[128:129], s[90:91], 0, v[168:169]
	s_add_u32 s68, s76, s68
	v_lshlrev_b64 v[128:129], 13, v[128:129]
	s_addc_u32 s69, s77, s69
	v_lshl_add_u64 v[128:129], s[68:69], 0, v[128:129]
	v_lshl_add_u64 v[128:129], s[42:43], 2, v[128:129]
	s_lshl_b32 s16, s18, 2
	v_lshl_add_u64 v[128:129], v[128:129], 0, s[16:17]
	v_lshl_add_u64 v[128:129], v[170:171], 2, v[128:129]
	v_pk_mul_f32 v[144:145], v[120:121], s[24:25] op_sel_hi:[1,0]
	s_mov_b32 s3, 0xffc00000
	s_mov_b32 s42, 0xffc00000
	s_mov_b32 s43, -1
	v_lshl_add_u64 v[132:133], v[128:129], 0, s[42:43]
	v_readlane_b32 s91, v255, 11
	s_waitcnt vmcnt(0)
	v_cvt_pk_f32_fp8_e32 v[138:139], v210
	v_cvt_pk_f32_fp8_sdwa v[136:137], v210 src0_sel:WORD_1
	v_cvt_pk_f32_fp8_e32 v[140:141], v211
	v_cvt_pk_f32_fp8_sdwa v[142:143], v211 src0_sel:WORD_1
	v_pk_mul_f32 v[134:135], v[122:123], s[24:25] op_sel_hi:[1,0]
	s_nop 0
	v_pk_mul_f32 v[136:137], v[134:135], v[136:137]
	v_pk_mul_f32 v[134:135], v[144:145], v[138:139]
	v_add_co_u32_e32 v138, vcc, s3, v128
	v_pk_mul_f32 v[144:145], v[88:89], s[24:25] op_sel_hi:[1,0]
	s_nop 0
	v_addc_co_u32_e32 v139, vcc, -1, v129, vcc
	global_store_dwordx4 v[138:139], v[134:137], off
	v_pk_mul_f32 v[138:139], v[124:125], s[24:25] op_sel_hi:[1,0]
	s_mov_b32 s3, 0x8000
	v_pk_mul_f32 v[134:135], v[126:127], s[24:25] op_sel_hi:[1,0]
	s_nop 0
	v_pk_mul_f32 v[136:137], v[134:135], v[142:143]
	v_pk_mul_f32 v[134:135], v[138:139], v[140:141]
	global_store_dwordx4 v[132:133], v[134:137], off offset:16
	s_nop 1
	v_cvt_pk_f32_fp8_e32 v[138:139], v212
	v_cvt_pk_f32_fp8_sdwa v[136:137], v212 src0_sel:WORD_1
	v_cvt_pk_f32_fp8_e32 v[140:141], v213
	v_cvt_pk_f32_fp8_sdwa v[142:143], v213 src0_sel:WORD_1
	v_pk_mul_f32 v[134:135], v[90:91], s[24:25] op_sel_hi:[1,0]
	s_nop 0
	v_pk_mul_f32 v[136:137], v[134:135], v[136:137]
	v_pk_mul_f32 v[134:135], v[144:145], v[138:139]
	global_store_dwordx4 v[132:133], v[134:137], off offset:512
	v_pk_mul_f32 v[138:139], v[92:93], s[24:25] op_sel_hi:[1,0]
	v_pk_mul_f32 v[144:145], v[112:113], s[24:25] op_sel_hi:[1,0]
	v_pk_mul_f32 v[134:135], v[94:95], s[24:25] op_sel_hi:[1,0]
	s_nop 0
	v_pk_mul_f32 v[136:137], v[134:135], v[142:143]
	v_pk_mul_f32 v[134:135], v[138:139], v[140:141]
	global_store_dwordx4 v[132:133], v[134:137], off offset:528
	s_nop 1
	v_add_co_u32_e32 v136, vcc, s3, v130
	s_mov_b32 s3, 0xffc20000
	s_nop 0
	v_addc_co_u32_e32 v137, vcc, 0, v131, vcc
	s_nop 1
	v_cvt_pk_f32_fp8_e32 v[138:139], v214
	v_cvt_pk_f32_fp8_sdwa v[134:135], v214 src0_sel:WORD_1
	v_cvt_pk_f32_fp8_e32 v[140:141], v215
	v_cvt_pk_f32_fp8_sdwa v[142:143], v215 src0_sel:WORD_1
	v_pk_mul_f32 v[132:133], v[114:115], s[24:25] op_sel_hi:[1,0]
	s_nop 0
	v_pk_mul_f32 v[134:135], v[132:133], v[134:135]
	v_pk_mul_f32 v[132:133], v[144:145], v[138:139]
	v_add_co_u32_e32 v138, vcc, s3, v128
	s_mov_b32 s3, 0xffc21000
	s_nop 0
	v_addc_co_u32_e32 v139, vcc, -1, v129, vcc
	global_store_dwordx4 v[138:139], v[132:135], off
	v_pk_mul_f32 v[138:139], v[116:117], s[24:25] op_sel_hi:[1,0]
	v_pk_mul_f32 v[144:145], v[80:81], s[24:25] op_sel_hi:[1,0]
	v_pk_mul_f32 v[132:133], v[118:119], s[24:25] op_sel_hi:[1,0]
	s_nop 0
	v_pk_mul_f32 v[134:135], v[132:133], v[142:143]
	v_pk_mul_f32 v[132:133], v[138:139], v[140:141]
	v_add_co_u32_e32 v138, vcc, s3, v128
	s_mov_b32 s3, 0x10000
	s_nop 0
	v_addc_co_u32_e32 v139, vcc, -1, v129, vcc
;     __device__ __forceinline__ void operator()(Acc& acc, const Unit& u, int wr, int wc, int fr, int fq) const {
;     ...
;             for (int ai = 0; ai < 2; ++ai)
; #pragma unroll
;                 for (int m = 0; m < 4; ++m)
; #pragma unroll
;                     for (int bj = 0; bj < 2; ++bj) { const size_t ro = (size_t)(ai * HALF + m * 16) * DM + bj * HALF;
;                         f32x4 g0, g1; fp8x8_to_f32(*(const u32x2*)(sg + ro), g0, g1);
;                         *(f32x4*)(sl + ro) = acc[ai][bj][m][0] * (1.0f / (O_SCALE * WO_SCALE * G_SCALE)) * g0;
;                         *(f32x4*)(sl + ro + 4) = acc[ai][bj][m][1] * (1.0f / (O_SCALE * WO_SCALE * G_SCALE)) * g1; }
	global_store_dwordx4 v[138:139], v[132:135], off offset:-4080
	s_nop 1
	v_cvt_pk_f32_fp8_e32 v[136:137], v216
	v_cvt_pk_f32_fp8_sdwa v[134:135], v216 src0_sel:WORD_1
	v_cvt_pk_f32_fp8_e32 v[140:141], v217
	v_cvt_pk_f32_fp8_sdwa v[142:143], v217 src0_sel:WORD_1
	v_pk_mul_f32 v[132:133], v[82:83], s[24:25] op_sel_hi:[1,0]
	s_nop 0
	v_pk_mul_f32 v[134:135], v[132:133], v[134:135]
	v_pk_mul_f32 v[132:133], v[144:145], v[136:137]
	global_store_dwordx4 v[138:139], v[132:135], off offset:-3584
	v_pk_mul_f32 v[136:137], v[84:85], s[24:25] op_sel_hi:[1,0]
	v_pk_mul_f32 v[144:145], v[104:105], s[24:25] op_sel_hi:[1,0]
	v_pk_mul_f32 v[132:133], v[86:87], s[24:25] op_sel_hi:[1,0]
	s_nop 0
	v_pk_mul_f32 v[134:135], v[132:133], v[142:143]
	v_pk_mul_f32 v[132:133], v[136:137], v[140:141]
	v_add_co_u32_e32 v136, vcc, s3, v130
	global_store_dwordx4 v[138:139], v[132:135], off offset:-3568
	s_nop 0
	v_addc_co_u32_e32 v137, vcc, 0, v131, vcc
	s_nop 1
	s_mov_b32 s3, 0xffc40000
	v_cvt_pk_f32_fp8_e32 v[138:139], v218
	v_cvt_pk_f32_fp8_sdwa v[134:135], v218 src0_sel:WORD_1
	v_cvt_pk_f32_fp8_e32 v[140:141], v219
	v_cvt_pk_f32_fp8_sdwa v[142:143], v219 src0_sel:WORD_1
	v_pk_mul_f32 v[132:133], v[106:107], s[24:25] op_sel_hi:[1,0]
	s_nop 0
	v_pk_mul_f32 v[134:135], v[132:133], v[134:135]
	v_pk_mul_f32 v[132:133], v[144:145], v[138:139]
	v_add_co_u32_e32 v138, vcc, s3, v128
	s_mov_b32 s3, 0xffc41000
	s_nop 0
	v_addc_co_u32_e32 v139, vcc, -1, v129, vcc
	global_store_dwordx4 v[138:139], v[132:135], off
	v_pk_mul_f32 v[138:139], v[108:109], s[24:25] op_sel_hi:[1,0]
	v_pk_mul_f32 v[144:145], v[72:73], s[24:25] op_sel_hi:[1,0]
	v_pk_mul_f32 v[132:133], v[110:111], s[24:25] op_sel_hi:[1,0]
	s_nop 0
	v_pk_mul_f32 v[134:135], v[132:133], v[142:143]
	v_pk_mul_f32 v[132:133], v[138:139], v[140:141]
	v_add_co_u32_e32 v138, vcc, s3, v128
	s_mov_b32 s3, 0x18000
	s_nop 0
	v_addc_co_u32_e32 v139, vcc, -1, v129, vcc
	global_store_dwordx4 v[138:139], v[132:135], off offset:-4080
	s_nop 1
	v_cvt_pk_f32_fp8_e32 v[136:137], v220
	v_cvt_pk_f32_fp8_sdwa v[134:135], v220 src0_sel:WORD_1
	v_cvt_pk_f32_fp8_e32 v[140:141], v221
	v_cvt_pk_f32_fp8_sdwa v[142:143], v221 src0_sel:WORD_1
	v_pk_mul_f32 v[132:133], v[74:75], s[24:25] op_sel_hi:[1,0]
	s_nop 0
	v_pk_mul_f32 v[134:135], v[132:133], v[134:135]
	v_pk_mul_f32 v[132:133], v[144:145], v[136:137]
	global_store_dwordx4 v[138:139], v[132:135], off offset:-3584
	v_pk_mul_f32 v[136:137], v[76:77], s[24:25] op_sel_hi:[1,0]
	v_pk_mul_f32 v[144:145], v[96:97], s[24:25] op_sel_hi:[1,0]
	v_pk_mul_f32 v[132:133], v[78:79], s[24:25] op_sel_hi:[1,0]
	s_nop 0
	v_pk_mul_f32 v[134:135], v[132:133], v[142:143]
	v_pk_mul_f32 v[132:133], v[136:137], v[140:141]
	v_add_co_u32_e32 v136, vcc, s3, v130
	global_store_dwordx4 v[138:139], v[132:135], off offset:-3568
	s_nop 0
	v_addc_co_u32_e32 v137, vcc, 0, v131, vcc
	s_nop 1
	s_mov_b32 s3, 0xffc60000
	v_cvt_pk_f32_fp8_e32 v[138:139], v222
	v_cvt_pk_f32_fp8_sdwa v[134:135], v222 src0_sel:WORD_1
	v_cvt_pk_f32_fp8_e32 v[140:141], v223
	v_cvt_pk_f32_fp8_sdwa v[142:143], v223 src0_sel:WORD_1
	v_pk_mul_f32 v[132:133], v[98:99], s[24:25] op_sel_hi:[1,0]
	s_nop 0
	v_pk_mul_f32 v[134:135], v[132:133], v[134:135]
	v_pk_mul_f32 v[132:133], v[144:145], v[138:139]
	v_add_co_u32_e32 v138, vcc, s3, v128
	s_mov_b32 s3, 0xffc61000
	s_nop 0
	v_addc_co_u32_e32 v139, vcc, -1, v129, vcc
	global_store_dwordx4 v[138:139], v[132:135], off
	v_pk_mul_f32 v[138:139], v[100:101], s[24:25] op_sel_hi:[1,0]
	v_pk_mul_f32 v[144:145], v[64:65], s[24:25] op_sel_hi:[1,0]
	v_pk_mul_f32 v[132:133], v[102:103], s[24:25] op_sel_hi:[1,0]
	s_nop 0
	v_pk_mul_f32 v[134:135], v[132:133], v[142:143]
	v_pk_mul_f32 v[132:133], v[138:139], v[140:141]
	v_add_co_u32_e32 v138, vcc, s3, v128
	s_mov_b32 s3, 0x40000
	s_nop 0
	v_addc_co_u32_e32 v139, vcc, -1, v129, vcc
	global_store_dwordx4 v[138:139], v[132:135], off offset:-4080
	s_nop 1
	v_cvt_pk_f32_fp8_e32 v[136:137], v224
	v_cvt_pk_f32_fp8_sdwa v[134:135], v224 src0_sel:WORD_1
	v_cvt_pk_f32_fp8_e32 v[140:141], v225
	v_cvt_pk_f32_fp8_sdwa v[142:143], v225 src0_sel:WORD_1
	v_pk_mul_f32 v[132:133], v[66:67], s[24:25] op_sel_hi:[1,0]
	s_nop 0
	v_pk_mul_f32 v[134:135], v[132:133], v[134:135]
	v_pk_mul_f32 v[132:133], v[144:145], v[136:137]
	global_store_dwordx4 v[138:139], v[132:135], off offset:-3584
	v_pk_mul_f32 v[136:137], v[68:69], s[24:25] op_sel_hi:[1,0]
	v_pk_mul_f32 v[144:145], v[56:57], s[24:25] op_sel_hi:[1,0]
	v_pk_mul_f32 v[132:133], v[70:71], s[24:25] op_sel_hi:[1,0]
	s_nop 0
	v_pk_mul_f32 v[134:135], v[132:133], v[142:143]
	v_pk_mul_f32 v[132:133], v[136:137], v[140:141]
	v_add_co_u32_e32 v136, vcc, s3, v130
	global_store_dwordx4 v[138:139], v[132:135], off offset:-3568
	s_nop 0
	v_addc_co_u32_e32 v137, vcc, 0, v131, vcc
	s_nop 1
	s_mov_b32 s3, 0xffd00000
	v_cvt_pk_f32_fp8_e32 v[138:139], v226
	v_cvt_pk_f32_fp8_sdwa v[134:135], v226 src0_sel:WORD_1
	v_cvt_pk_f32_fp8_e32 v[140:141], v227
	v_cvt_pk_f32_fp8_sdwa v[142:143], v227 src0_sel:WORD_1
	v_pk_mul_f32 v[132:133], v[58:59], s[24:25] op_sel_hi:[1,0]
	s_nop 0
	v_pk_mul_f32 v[134:135], v[132:133], v[134:135]
	v_pk_mul_f32 v[132:133], v[144:145], v[138:139]
	v_add_co_u32_e32 v138, vcc, s3, v128
	s_mov_b32 s3, 0xffd01000
	s_nop 0
	v_addc_co_u32_e32 v139, vcc, -1, v129, vcc
	global_store_dwordx4 v[138:139], v[132:135], off
	v_pk_mul_f32 v[138:139], v[60:61], s[24:25] op_sel_hi:[1,0]
	v_pk_mul_f32 v[144:145], v[24:25], s[24:25] op_sel_hi:[1,0]
	v_pk_mul_f32 v[132:133], v[62:63], s[24:25] op_sel_hi:[1,0]
	s_nop 0
	v_pk_mul_f32 v[134:135], v[132:133], v[142:143]
	v_pk_mul_f32 v[132:133], v[138:139], v[140:141]
	v_add_co_u32_e32 v138, vcc, s3, v128
;     __device__ __forceinline__ void operator()(Acc& acc, const Unit& u, int wr, int wc, int fr, int fq) const {
;     ...
;             for (int ai = 0; ai < 2; ++ai)
; #pragma unroll
;                 for (int m = 0; m < 4; ++m)
; #pragma unroll
;                     for (int bj = 0; bj < 2; ++bj) { const size_t ro = (size_t)(ai * HALF + m * 16) * DM + bj * HALF;
;                         f32x4 g0, g1; fp8x8_to_f32(*(const u32x2*)(sg + ro), g0, g1);
;                         *(f32x4*)(sl + ro) = acc[ai][bj][m][0] * (1.0f / (O_SCALE * WO_SCALE * G_SCALE)) * g0;
;                         *(f32x4*)(sl + ro + 4) = acc[ai][bj][m][1] * (1.0f / (O_SCALE * WO_SCALE * G_SCALE)) * g1; }
;             return;
	s_mov_b32 s3, 0x48000
	s_nop 0
	v_addc_co_u32_e32 v139, vcc, -1, v129, vcc
	global_store_dwordx4 v[138:139], v[132:135], off offset:-4080
	s_nop 1
	v_cvt_pk_f32_fp8_e32 v[136:137], v228
	v_cvt_pk_f32_fp8_sdwa v[134:135], v228 src0_sel:WORD_1
	v_cvt_pk_f32_fp8_e32 v[140:141], v229
	v_cvt_pk_f32_fp8_sdwa v[142:143], v229 src0_sel:WORD_1
	v_pk_mul_f32 v[132:133], v[26:27], s[24:25] op_sel_hi:[1,0]
	s_nop 0
	v_pk_mul_f32 v[134:135], v[132:133], v[134:135]
	v_pk_mul_f32 v[132:133], v[144:145], v[136:137]
	global_store_dwordx4 v[138:139], v[132:135], off offset:-3584
	v_pk_mul_f32 v[136:137], v[28:29], s[24:25] op_sel_hi:[1,0]
	v_pk_mul_f32 v[144:145], v[48:49], s[24:25] op_sel_hi:[1,0]
	v_pk_mul_f32 v[132:133], v[30:31], s[24:25] op_sel_hi:[1,0]
	s_nop 0
	v_pk_mul_f32 v[134:135], v[132:133], v[142:143]
	v_pk_mul_f32 v[132:133], v[136:137], v[140:141]
	v_add_co_u32_e32 v136, vcc, s3, v130
	global_store_dwordx4 v[138:139], v[132:135], off offset:-3568
	s_nop 0
	v_addc_co_u32_e32 v137, vcc, 0, v131, vcc
	s_nop 1
	s_mov_b32 s3, 0xffd20000
	v_cvt_pk_f32_fp8_e32 v[138:139], v230
	v_cvt_pk_f32_fp8_sdwa v[134:135], v230 src0_sel:WORD_1
	v_cvt_pk_f32_fp8_e32 v[140:141], v231
	v_cvt_pk_f32_fp8_sdwa v[142:143], v231 src0_sel:WORD_1
	v_pk_mul_f32 v[132:133], v[50:51], s[24:25] op_sel_hi:[1,0]
	s_nop 0
	v_pk_mul_f32 v[134:135], v[132:133], v[134:135]
	v_pk_mul_f32 v[132:133], v[144:145], v[138:139]
	v_add_co_u32_e32 v138, vcc, s3, v128
	s_mov_b32 s3, 0xffd21000
	s_nop 0
	v_addc_co_u32_e32 v139, vcc, -1, v129, vcc
	global_store_dwordx4 v[138:139], v[132:135], off
	v_pk_mul_f32 v[138:139], v[52:53], s[24:25] op_sel_hi:[1,0]
	v_pk_mul_f32 v[144:145], v[16:17], s[24:25] op_sel_hi:[1,0]
	v_pk_mul_f32 v[132:133], v[54:55], s[24:25] op_sel_hi:[1,0]
	s_nop 0
	v_pk_mul_f32 v[134:135], v[132:133], v[142:143]
	v_pk_mul_f32 v[132:133], v[138:139], v[140:141]
	v_add_co_u32_e32 v138, vcc, s3, v128
	s_mov_b32 s3, 0x50000
	s_nop 0
	v_addc_co_u32_e32 v139, vcc, -1, v129, vcc
	global_store_dwordx4 v[138:139], v[132:135], off offset:-4080
	s_nop 1
	v_cvt_pk_f32_fp8_e32 v[136:137], v232
	v_cvt_pk_f32_fp8_sdwa v[134:135], v232 src0_sel:WORD_1
	v_cvt_pk_f32_fp8_e32 v[140:141], v233
	v_cvt_pk_f32_fp8_sdwa v[142:143], v233 src0_sel:WORD_1
	v_pk_mul_f32 v[132:133], v[18:19], s[24:25] op_sel_hi:[1,0]
	s_nop 0
	v_pk_mul_f32 v[134:135], v[132:133], v[134:135]
	v_pk_mul_f32 v[132:133], v[144:145], v[136:137]
	global_store_dwordx4 v[138:139], v[132:135], off offset:-3584
	v_pk_mul_f32 v[136:137], v[20:21], s[24:25] op_sel_hi:[1,0]
	v_pk_mul_f32 v[144:145], v[40:41], s[24:25] op_sel_hi:[1,0]
	v_pk_mul_f32 v[132:133], v[22:23], s[24:25] op_sel_hi:[1,0]
	s_nop 0
	v_pk_mul_f32 v[134:135], v[132:133], v[142:143]
	v_pk_mul_f32 v[132:133], v[136:137], v[140:141]
	v_add_co_u32_e32 v136, vcc, s3, v130
	global_store_dwordx4 v[138:139], v[132:135], off offset:-3568
	s_nop 0
	v_addc_co_u32_e32 v137, vcc, 0, v131, vcc
	s_nop 1
	s_mov_b32 s3, 0xffd40000
	v_cvt_pk_f32_fp8_e32 v[138:139], v234
	v_cvt_pk_f32_fp8_sdwa v[134:135], v234 src0_sel:WORD_1
	v_cvt_pk_f32_fp8_e32 v[140:141], v235
	v_cvt_pk_f32_fp8_sdwa v[142:143], v235 src0_sel:WORD_1
	v_pk_mul_f32 v[132:133], v[42:43], s[24:25] op_sel_hi:[1,0]
	s_nop 0
	v_pk_mul_f32 v[134:135], v[132:133], v[134:135]
	v_pk_mul_f32 v[132:133], v[144:145], v[138:139]
	v_add_co_u32_e32 v138, vcc, s3, v128
	s_mov_b32 s3, 0xffd41000
	s_nop 0
	v_addc_co_u32_e32 v139, vcc, -1, v129, vcc
	global_store_dwordx4 v[138:139], v[132:135], off
	v_pk_mul_f32 v[138:139], v[44:45], s[24:25] op_sel_hi:[1,0]
	v_pk_mul_f32 v[144:145], v[8:9], s[24:25] op_sel_hi:[1,0]
	v_pk_mul_f32 v[132:133], v[46:47], s[24:25] op_sel_hi:[1,0]
	s_nop 0
	v_pk_mul_f32 v[134:135], v[132:133], v[142:143]
	v_pk_mul_f32 v[132:133], v[138:139], v[140:141]
	v_add_co_u32_e32 v138, vcc, s3, v128
	s_mov_b32 s3, 0x58000
	s_nop 0
	v_addc_co_u32_e32 v139, vcc, -1, v129, vcc
	global_store_dwordx4 v[138:139], v[132:135], off offset:-4080
	s_nop 1
	v_cvt_pk_f32_fp8_e32 v[136:137], v236
	v_cvt_pk_f32_fp8_sdwa v[134:135], v236 src0_sel:WORD_1
	v_cvt_pk_f32_fp8_e32 v[140:141], v237
	v_cvt_pk_f32_fp8_sdwa v[142:143], v237 src0_sel:WORD_1
	v_pk_mul_f32 v[132:133], v[10:11], s[24:25] op_sel_hi:[1,0]
	s_nop 0
	v_pk_mul_f32 v[134:135], v[132:133], v[134:135]
	v_pk_mul_f32 v[132:133], v[144:145], v[136:137]
	global_store_dwordx4 v[138:139], v[132:135], off offset:-3584
	v_pk_mul_f32 v[136:137], v[12:13], s[24:25] op_sel_hi:[1,0]
	s_nop 0
	v_pk_mul_f32 v[132:133], v[14:15], s[24:25] op_sel_hi:[1,0]
	s_nop 0
	v_pk_mul_f32 v[134:135], v[132:133], v[142:143]
	v_pk_mul_f32 v[132:133], v[136:137], v[140:141]
	global_store_dwordx4 v[138:139], v[132:135], off offset:-3568
	v_pk_mul_f32 v[142:143], v[32:33], s[24:25] op_sel_hi:[1,0]
	s_nop 0
	v_add_co_u32_e32 v134, vcc, s3, v130
	s_nop 1
	v_addc_co_u32_e32 v135, vcc, 0, v131, vcc
	s_nop 1
	v_cvt_pk_f32_fp8_e32 v[136:137], v238
	v_cvt_pk_f32_fp8_sdwa v[132:133], v238 src0_sel:WORD_1
	v_cvt_pk_f32_fp8_e32 v[138:139], v239
	v_cvt_pk_f32_fp8_sdwa v[140:141], v239 src0_sel:WORD_1
	v_pk_mul_f32 v[130:131], v[34:35], s[24:25] op_sel_hi:[1,0]
	s_nop 0
	v_pk_mul_f32 v[132:133], v[130:131], v[132:133]
	v_pk_mul_f32 v[130:131], v[142:143], v[136:137]
	v_add_co_u32_e32 v136, vcc, s85, v128
	s_nop 1
	v_addc_co_u32_e32 v137, vcc, -1, v129, vcc
	global_store_dwordx4 v[136:137], v[130:133], off
	v_pk_mul_f32 v[136:137], v[36:37], s[24:25] op_sel_hi:[1,0]
	s_nop 0
	v_pk_mul_f32 v[130:131], v[38:39], s[24:25] op_sel_hi:[1,0]
	s_nop 0
	v_pk_mul_f32 v[132:133], v[130:131], v[140:141]
	v_pk_mul_f32 v[130:131], v[136:137], v[138:139]
	v_add_co_u32_e32 v136, vcc, s86, v128
	v_pk_mul_f32 v[140:141], v[0:1], s[24:25] op_sel_hi:[1,0]
	s_nop 0
	v_addc_co_u32_e32 v137, vcc, -1, v129, vcc
	global_store_dwordx4 v[136:137], v[130:133], off offset:-4080
	s_nop 1
	v_cvt_pk_f32_fp8_e32 v[134:135], v241
	v_cvt_pk_f32_fp8_e32 v[132:133], v240
	v_cvt_pk_f32_fp8_sdwa v[130:131], v240 src0_sel:WORD_1
	v_cvt_pk_f32_fp8_sdwa v[138:139], v241 src0_sel:WORD_1
	v_pk_mul_f32 v[128:129], v[2:3], s[24:25] op_sel_hi:[1,0]
	s_nop 0
	v_pk_mul_f32 v[130:131], v[128:129], v[130:131]
	v_pk_mul_f32 v[128:129], v[140:141], v[132:133]
	global_store_dwordx4 v[136:137], v[128:131], off offset:-3584
	v_pk_mul_f32 v[132:133], v[4:5], s[24:25] op_sel_hi:[1,0]
	s_nop 0
	v_pk_mul_f32 v[128:129], v[6:7], s[24:25] op_sel_hi:[1,0]
	s_nop 0
	v_pk_mul_f32 v[130:131], v[128:129], v[138:139]
	v_pk_mul_f32 v[128:129], v[132:133], v[134:135]
	global_store_dwordx4 v[136:137], v[128:131], off offset:-3568
	s_cbranch_execz .LBB0_2064
	s_branch .LBB0_2158
